# residual GEMM epilogues: lane exchange (DPP row_ror:8 + masked v_swap) so each residual load/store covers whole 128-byte lines (8 rows x 128 B per instruction)
# baseline (speedup 1.0000x reference)
.LBB0_133:
	s_add_u32 s28, s22, 0x100
	s_addc_u32 s29, s23, 0
	s_add_i32 s85, 0, 0x10000
	v_add_u32_e32 v148, s85, v157
	ds_read_b128 v[130:133], v148
	ds_read_b128 v[134:137], v148 offset:1024
	ds_read_b128 v[138:141], v148 offset:2048
	ds_read_b128 v[148:151], v148 offset:3072
	s_cmp_eq_u32 s84, 40
	s_cselect_b32 s43, s17, s29
	s_cselect_b32 s42, s16, s28
	s_cselect_b32 s41, s19, s79
	s_cselect_b32 s40, s18, s34
	v_lshl_add_u64 v[188:189], s[22:23], 0, v[146:147]
	s_add_i32 m0, s54, 0xc000
	ds_read_b128 v[152:155], v159
	ds_read_b128 v[160:163], v159 offset:1024
	ds_read_b128 v[164:167], v159 offset:2048
	ds_read_b128 v[168:171], v159 offset:3072
	ds_read_b128 v[172:175], v159 offset:4096
	ds_read_b128 v[176:179], v159 offset:5120
	ds_read_b128 v[180:183], v159 offset:6144
	ds_read_b128 v[184:187], v159 offset:7168
	global_load_lds_dwordx4 v[188:189], off
	v_lshl_add_u64 v[188:189], s[22:23], 0, v[144:145]
	s_add_i32 m0, s54, 0xe000
	s_nop 0
	global_load_lds_dwordx4 v[188:189], off
	s_waitcnt lgkmcnt(8)
	s_waitcnt vmcnt(10)
	s_barrier
	s_waitcnt lgkmcnt(0)
	s_waitcnt lgkmcnt(0)
	v_mfma_f32_16x16x32_bf16 v[126:129], v[130:133], v[152:155], v[126:129]
	v_mfma_f32_16x16x32_bf16 v[122:125], v[138:141], v[152:155], v[122:125]
	v_mfma_f32_16x16x32_bf16 v[118:121], v[130:133], v[164:167], v[118:121]
	v_mfma_f32_16x16x32_bf16 v[106:109], v[138:141], v[164:167], v[106:109]
	v_mfma_f32_16x16x32_bf16 v[102:105], v[130:133], v[172:175], v[102:105]
	v_mfma_f32_16x16x32_bf16 v[90:93], v[138:141], v[172:175], v[90:93]
	v_mfma_f32_16x16x32_bf16 v[86:89], v[130:133], v[180:183], v[86:89]
	v_mfma_f32_16x16x32_bf16 v[74:77], v[138:141], v[180:183], v[74:77]
	v_mfma_f32_16x16x32_bf16 v[126:129], v[134:137], v[160:163], v[126:129]
	v_mfma_f32_16x16x32_bf16 v[122:125], v[148:151], v[160:163], v[122:125]
	v_mfma_f32_16x16x32_bf16 v[118:121], v[134:137], v[168:171], v[118:121]
	v_mfma_f32_16x16x32_bf16 v[106:109], v[148:151], v[168:171], v[106:109]
	v_mfma_f32_16x16x32_bf16 v[102:105], v[134:137], v[176:179], v[102:105]
	v_mfma_f32_16x16x32_bf16 v[90:93], v[148:151], v[176:179], v[90:93]
	v_mfma_f32_16x16x32_bf16 v[86:89], v[134:137], v[184:187], v[86:89]
	v_mfma_f32_16x16x32_bf16 v[74:77], v[148:151], v[184:187], v[74:77]
	s_barrier
	s_add_i32 s86, 0, 0x14000
	v_add_u32_e32 v196, s86, v157
	s_add_i32 s22, s85, s50
	ds_read_b128 v[188:191], v196
	ds_read_b128 v[192:195], v196 offset:1024
	ds_read_b128 v[208:211], v196 offset:2048
	ds_read_b128 v[212:215], v196 offset:3072
	v_lshl_add_u64 v[196:197], s[40:41], 0, v[16:17]
	s_mov_b32 m0, s22
	v_lshl_add_u64 v[216:217], s[40:41], 0, v[142:143]
	global_load_lds_dwordx4 v[196:197], off
	s_add_i32 m0, s22, 0x2000
	s_nop 0
	global_load_lds_dwordx4 v[216:217], off
	s_waitcnt vmcnt(10)
	s_barrier
	s_waitcnt lgkmcnt(0)
	s_waitcnt lgkmcnt(0)
	v_mfma_f32_16x16x32_bf16 v[114:117], v[188:191], v[152:155], v[114:117]
	v_mfma_f32_16x16x32_bf16 v[110:113], v[208:211], v[152:155], v[110:113]
	v_mfma_f32_16x16x32_bf16 v[98:101], v[188:191], v[164:167], v[98:101]
	v_mfma_f32_16x16x32_bf16 v[94:97], v[208:211], v[164:167], v[94:97]
	v_mfma_f32_16x16x32_bf16 v[82:85], v[188:191], v[172:175], v[82:85]
	v_mfma_f32_16x16x32_bf16 v[78:81], v[208:211], v[172:175], v[78:81]
	v_mfma_f32_16x16x32_bf16 v[70:73], v[188:191], v[180:183], v[70:73]
	v_mfma_f32_16x16x32_bf16 v[66:69], v[208:211], v[180:183], v[66:69]
	v_mfma_f32_16x16x32_bf16 v[114:117], v[192:195], v[160:163], v[114:117]
	v_mfma_f32_16x16x32_bf16 v[110:113], v[212:215], v[160:163], v[110:113]
	v_mfma_f32_16x16x32_bf16 v[98:101], v[192:195], v[168:171], v[98:101]
	v_mfma_f32_16x16x32_bf16 v[94:97], v[212:215], v[168:171], v[94:97]
	v_mfma_f32_16x16x32_bf16 v[82:85], v[192:195], v[176:179], v[82:85]
	v_mfma_f32_16x16x32_bf16 v[78:81], v[212:215], v[176:179], v[78:81]
	v_mfma_f32_16x16x32_bf16 v[70:73], v[192:195], v[184:187], v[70:73]
	v_mfma_f32_16x16x32_bf16 v[66:69], v[212:215], v[184:187], v[66:69]
	s_mov_b32 m0, s54
	v_lshl_add_u64 v[218:219], s[42:43], 0, v[16:17]
	s_barrier
	ds_read_b128 v[152:155], v159 offset:16384
	ds_read_b128 v[160:163], v159 offset:17408
	ds_read_b128 v[164:167], v159 offset:18432
	ds_read_b128 v[168:171], v159 offset:19456
	ds_read_b128 v[172:175], v159 offset:20480
	ds_read_b128 v[176:179], v159 offset:21504
	ds_read_b128 v[180:183], v159 offset:22528
	ds_read_b128 v[184:187], v159 offset:23552
	global_load_lds_dwordx4 v[218:219], off
	v_lshl_add_u64 v[220:221], s[42:43], 0, v[142:143]
	s_mov_b32 m0, s55
	s_nop 0
	global_load_lds_dwordx4 v[220:221], off
	s_barrier
	s_waitcnt lgkmcnt(0)
	s_waitcnt lgkmcnt(0)
	v_mfma_f32_16x16x32_bf16 v[62:65], v[130:133], v[152:155], v[62:65]
	v_mfma_f32_16x16x32_bf16 v[58:61], v[138:141], v[152:155], v[58:61]
	v_mfma_f32_16x16x32_bf16 v[54:57], v[130:133], v[164:167], v[54:57]
	v_mfma_f32_16x16x32_bf16 v[50:53], v[138:141], v[164:167], v[50:53]
	v_mfma_f32_16x16x32_bf16 v[46:49], v[130:133], v[172:175], v[46:49]
	v_mfma_f32_16x16x32_bf16 v[38:41], v[138:141], v[172:175], v[38:41]
	v_mfma_f32_16x16x32_bf16 v[30:33], v[130:133], v[180:183], v[30:33]
	v_mfma_f32_16x16x32_bf16 v[18:21], v[138:141], v[180:183], v[18:21]
	v_mfma_f32_16x16x32_bf16 v[62:65], v[134:137], v[160:163], v[62:65]
	v_mfma_f32_16x16x32_bf16 v[58:61], v[148:151], v[160:163], v[58:61]
	v_mfma_f32_16x16x32_bf16 v[54:57], v[134:137], v[168:171], v[54:57]
	v_mfma_f32_16x16x32_bf16 v[50:53], v[148:151], v[168:171], v[50:53]
	v_mfma_f32_16x16x32_bf16 v[46:49], v[134:137], v[176:179], v[46:49]
	v_mfma_f32_16x16x32_bf16 v[38:41], v[148:151], v[176:179], v[38:41]
	v_mfma_f32_16x16x32_bf16 v[30:33], v[134:137], v[184:187], v[30:33]
	v_mfma_f32_16x16x32_bf16 v[18:21], v[148:151], v[184:187], v[18:21]
	s_barrier
	s_add_u32 s22, s40, 0xb0000
	s_addc_u32 s23, s41, 0
	s_add_i32 s85, s86, s50
	v_lshl_add_u64 v[130:131], s[22:23], 0, v[16:17]
	s_mov_b32 m0, s85
	s_nop 0
	global_load_lds_dwordx4 v[130:131], off
	v_lshl_add_u64 v[130:131], s[22:23], 0, v[142:143]
	s_add_i32 m0, s85, 0x2000
	s_nop 0
	global_load_lds_dwordx4 v[130:131], off
	s_waitcnt vmcnt(10)
	s_barrier
	v_mfma_f32_16x16x32_bf16 v[42:45], v[188:191], v[152:155], v[42:45]
	v_mfma_f32_16x16x32_bf16 v[34:37], v[208:211], v[152:155], v[34:37]
	v_mfma_f32_16x16x32_bf16 v[26:29], v[188:191], v[164:167], v[26:29]
	v_mfma_f32_16x16x32_bf16 v[22:25], v[208:211], v[164:167], v[22:25]
	v_mfma_f32_16x16x32_bf16 v[12:15], v[188:191], v[172:175], v[12:15]
	v_mfma_f32_16x16x32_bf16 v[8:11], v[208:211], v[172:175], v[8:11]
	v_mfma_f32_16x16x32_bf16 v[4:7], v[188:191], v[180:183], v[4:7]
	v_mfma_f32_16x16x32_bf16 v[0:3], v[208:211], v[180:183], v[0:3]
	v_mfma_f32_16x16x32_bf16 v[42:45], v[192:195], v[160:163], v[42:45]
	v_mfma_f32_16x16x32_bf16 v[34:37], v[212:215], v[160:163], v[34:37]
	v_mfma_f32_16x16x32_bf16 v[26:29], v[192:195], v[168:171], v[26:29]
	v_mfma_f32_16x16x32_bf16 v[22:25], v[212:215], v[168:171], v[22:25]
	v_mfma_f32_16x16x32_bf16 v[12:15], v[192:195], v[176:179], v[12:15]
	v_mfma_f32_16x16x32_bf16 v[8:11], v[212:215], v[176:179], v[8:11]
	v_mfma_f32_16x16x32_bf16 v[4:7], v[192:195], v[184:187], v[4:7]
	v_mfma_f32_16x16x32_bf16 v[0:3], v[212:215], v[184:187], v[0:3]
	s_add_i32 s85, 0, 0x18000
	v_add_u32_e32 v148, s85, v157
	s_barrier
	ds_read_b128 v[130:133], v148
	ds_read_b128 v[134:137], v148 offset:1024
	ds_read_b128 v[138:141], v148 offset:2048
	ds_read_b128 v[148:151], v148 offset:3072
	s_add_u32 s22, s42, 0xb0000
	s_addc_u32 s23, s43, 0
	s_mov_b32 m0, s56
	v_lshl_add_u64 v[188:189], s[22:23], 0, v[16:17]
	ds_read_b128 v[152:155], v159 offset:32768
	ds_read_b128 v[160:163], v159 offset:33792
	ds_read_b128 v[164:167], v159 offset:34816
	ds_read_b128 v[168:171], v159 offset:35840
	ds_read_b128 v[172:175], v159 offset:36864
	ds_read_b128 v[176:179], v159 offset:37888
	ds_read_b128 v[180:183], v159 offset:38912
	ds_read_b128 v[184:187], v159 offset:39936
	global_load_lds_dwordx4 v[188:189], off
	v_lshl_add_u64 v[188:189], s[22:23], 0, v[142:143]
	s_mov_b32 m0, s57
	s_nop 0
	global_load_lds_dwordx4 v[188:189], off
	s_waitcnt lgkmcnt(8)
	s_waitcnt vmcnt(10)
	s_barrier
	s_waitcnt lgkmcnt(0)
	s_waitcnt lgkmcnt(0)
	v_mfma_f32_16x16x32_bf16 v[126:129], v[130:133], v[152:155], v[126:129]
	v_mfma_f32_16x16x32_bf16 v[122:125], v[138:141], v[152:155], v[122:125]
	v_mfma_f32_16x16x32_bf16 v[118:121], v[130:133], v[164:167], v[118:121]
	v_mfma_f32_16x16x32_bf16 v[106:109], v[138:141], v[164:167], v[106:109]
	v_mfma_f32_16x16x32_bf16 v[102:105], v[130:133], v[172:175], v[102:105]
	v_mfma_f32_16x16x32_bf16 v[90:93], v[138:141], v[172:175], v[90:93]
	v_mfma_f32_16x16x32_bf16 v[86:89], v[130:133], v[180:183], v[86:89]
	v_mfma_f32_16x16x32_bf16 v[74:77], v[138:141], v[180:183], v[74:77]
	v_mfma_f32_16x16x32_bf16 v[126:129], v[134:137], v[160:163], v[126:129]
	v_mfma_f32_16x16x32_bf16 v[122:125], v[148:151], v[160:163], v[122:125]
	v_mfma_f32_16x16x32_bf16 v[118:121], v[134:137], v[168:171], v[118:121]
	v_mfma_f32_16x16x32_bf16 v[106:109], v[148:151], v[168:171], v[106:109]
	v_mfma_f32_16x16x32_bf16 v[102:105], v[134:137], v[176:179], v[102:105]
	v_mfma_f32_16x16x32_bf16 v[90:93], v[148:151], v[176:179], v[90:93]
	v_mfma_f32_16x16x32_bf16 v[86:89], v[134:137], v[184:187], v[86:89]
	v_mfma_f32_16x16x32_bf16 v[74:77], v[148:151], v[184:187], v[74:77]
	s_barrier
	s_add_i32 s42, 0, 0x1c000
	s_add_i32 s22, s85, s50
	v_add_u32_e32 v212, s42, v157
	v_lshl_add_u64 v[196:197], v[196:197], 0, s[10:11]
	s_mov_b32 m0, s22
	ds_read_b128 v[188:191], v212
	ds_read_b128 v[192:195], v212 offset:1024
	ds_read_b128 v[208:211], v212 offset:2048
	ds_read_b128 v[212:215], v212 offset:3072
	global_load_lds_dwordx4 v[196:197], off
	v_lshl_add_u64 v[196:197], v[216:217], 0, s[10:11]
	s_add_i32 m0, s22, 0x2000
	s_nop 0
	global_load_lds_dwordx4 v[196:197], off
	s_waitcnt vmcnt(10)
	s_barrier
	s_waitcnt lgkmcnt(0)
	s_waitcnt lgkmcnt(0)
	v_mfma_f32_16x16x32_bf16 v[114:117], v[188:191], v[152:155], v[114:117]
	v_mfma_f32_16x16x32_bf16 v[110:113], v[208:211], v[152:155], v[110:113]
	v_mfma_f32_16x16x32_bf16 v[98:101], v[188:191], v[164:167], v[98:101]
	v_mfma_f32_16x16x32_bf16 v[94:97], v[208:211], v[164:167], v[94:97]
	v_mfma_f32_16x16x32_bf16 v[82:85], v[188:191], v[172:175], v[82:85]
	v_mfma_f32_16x16x32_bf16 v[78:81], v[208:211], v[172:175], v[78:81]
	v_mfma_f32_16x16x32_bf16 v[70:73], v[188:191], v[180:183], v[70:73]
	v_mfma_f32_16x16x32_bf16 v[66:69], v[208:211], v[180:183], v[66:69]
	v_mfma_f32_16x16x32_bf16 v[114:117], v[192:195], v[160:163], v[114:117]
	v_mfma_f32_16x16x32_bf16 v[110:113], v[212:215], v[160:163], v[110:113]
	v_mfma_f32_16x16x32_bf16 v[98:101], v[192:195], v[168:171], v[98:101]
	v_mfma_f32_16x16x32_bf16 v[94:97], v[212:215], v[168:171], v[94:97]
	v_mfma_f32_16x16x32_bf16 v[82:85], v[192:195], v[176:179], v[82:85]
	v_mfma_f32_16x16x32_bf16 v[78:81], v[212:215], v[176:179], v[78:81]
	v_mfma_f32_16x16x32_bf16 v[70:73], v[192:195], v[184:187], v[70:73]
	v_mfma_f32_16x16x32_bf16 v[66:69], v[212:215], v[184:187], v[66:69]
	s_mov_b32 m0, s58
	v_lshl_add_u64 v[196:197], v[218:219], 0, s[10:11]
	s_barrier
	ds_read_b128 v[152:155], v159 offset:49152
	ds_read_b128 v[160:163], v159 offset:50176
	ds_read_b128 v[164:167], v159 offset:51200
	ds_read_b128 v[168:171], v159 offset:52224
	ds_read_b128 v[172:175], v159 offset:53248
	ds_read_b128 v[176:179], v159 offset:54272
	ds_read_b128 v[180:183], v159 offset:55296
	ds_read_b128 v[184:187], v159 offset:56320
	global_load_lds_dwordx4 v[196:197], off
	v_lshl_add_u64 v[196:197], v[220:221], 0, s[10:11]
	s_mov_b32 m0, s59
	s_nop 0
	global_load_lds_dwordx4 v[196:197], off
	s_barrier
	s_waitcnt lgkmcnt(0)
	s_waitcnt lgkmcnt(0)
	v_mfma_f32_16x16x32_bf16 v[62:65], v[130:133], v[152:155], v[62:65]
	v_mfma_f32_16x16x32_bf16 v[58:61], v[138:141], v[152:155], v[58:61]
	v_mfma_f32_16x16x32_bf16 v[54:57], v[130:133], v[164:167], v[54:57]
	v_mfma_f32_16x16x32_bf16 v[50:53], v[138:141], v[164:167], v[50:53]
	v_mfma_f32_16x16x32_bf16 v[46:49], v[130:133], v[172:175], v[46:49]
	v_mfma_f32_16x16x32_bf16 v[38:41], v[138:141], v[172:175], v[38:41]
	v_mfma_f32_16x16x32_bf16 v[30:33], v[130:133], v[180:183], v[30:33]
	v_mfma_f32_16x16x32_bf16 v[18:21], v[138:141], v[180:183], v[18:21]
	v_mfma_f32_16x16x32_bf16 v[62:65], v[134:137], v[160:163], v[62:65]
	v_mfma_f32_16x16x32_bf16 v[58:61], v[148:151], v[160:163], v[58:61]
	v_mfma_f32_16x16x32_bf16 v[54:57], v[134:137], v[168:171], v[54:57]
	v_mfma_f32_16x16x32_bf16 v[50:53], v[148:151], v[168:171], v[50:53]
	v_mfma_f32_16x16x32_bf16 v[46:49], v[134:137], v[176:179], v[46:49]
	v_mfma_f32_16x16x32_bf16 v[38:41], v[148:151], v[176:179], v[38:41]
	v_mfma_f32_16x16x32_bf16 v[30:33], v[134:137], v[184:187], v[30:33]
	v_mfma_f32_16x16x32_bf16 v[18:21], v[148:151], v[184:187], v[18:21]
	s_barrier
	s_add_u32 s22, s40, 0xb0080
	s_addc_u32 s23, s41, 0
	s_add_i32 s40, s42, s50
	v_lshl_add_u64 v[130:131], s[22:23], 0, v[16:17]
	s_mov_b32 m0, s40
	s_nop 0
	global_load_lds_dwordx4 v[130:131], off
	v_lshl_add_u64 v[130:131], s[22:23], 0, v[142:143]
	s_add_i32 m0, s40, 0x2000
	s_nop 0
	global_load_lds_dwordx4 v[130:131], off
	s_waitcnt vmcnt(10)
	s_barrier
	v_mfma_f32_16x16x32_bf16 v[42:45], v[188:191], v[152:155], v[42:45]
	v_mfma_f32_16x16x32_bf16 v[34:37], v[208:211], v[152:155], v[34:37]
	v_mfma_f32_16x16x32_bf16 v[26:29], v[188:191], v[164:167], v[26:29]
	v_mfma_f32_16x16x32_bf16 v[22:25], v[208:211], v[164:167], v[22:25]
	v_mfma_f32_16x16x32_bf16 v[12:15], v[188:191], v[172:175], v[12:15]
	v_mfma_f32_16x16x32_bf16 v[8:11], v[208:211], v[172:175], v[8:11]
	v_mfma_f32_16x16x32_bf16 v[4:7], v[188:191], v[180:183], v[4:7]
	v_mfma_f32_16x16x32_bf16 v[0:3], v[208:211], v[180:183], v[0:3]
	v_mfma_f32_16x16x32_bf16 v[42:45], v[192:195], v[160:163], v[42:45]
	v_mfma_f32_16x16x32_bf16 v[34:37], v[212:215], v[160:163], v[34:37]
	v_mfma_f32_16x16x32_bf16 v[26:29], v[192:195], v[168:171], v[26:29]
	v_mfma_f32_16x16x32_bf16 v[22:25], v[212:215], v[168:171], v[22:25]
	v_mfma_f32_16x16x32_bf16 v[12:15], v[192:195], v[176:179], v[12:15]
	v_mfma_f32_16x16x32_bf16 v[8:11], v[212:215], v[176:179], v[8:11]
	v_mfma_f32_16x16x32_bf16 v[4:7], v[192:195], v[184:187], v[4:7]
	v_mfma_f32_16x16x32_bf16 v[0:3], v[212:215], v[184:187], v[0:3]
	s_add_i32 s84, s84, 2
	s_add_u32 s34, s34, 0x100
	s_addc_u32 s79, s79, 0
	s_cmp_gt_u32 s84, 41
	s_mov_b64 s[22:23], s[28:29]
	s_barrier
	s_cbranch_scc0 .LBB0_133
	v_lshl_or_b32 v242, s12, 8, v158
	v_lshl_add_u32 v243, s2, 8, v156
	v_lshlrev_b32_e32 v242, 2, v242
	v_lshl_add_u32 v242, v243, 12, v242
	v_and_b32_e32 v243, 8, v156
	v_mul_u32_u24_e32 v244, 0xff8, v243
	v_sub_u32_e32 v148, v242, v244
	v_sub_u32_e32 v243, 8, v243
	v_mul_u32_u24_e32 v244, 0x1008, v243
	v_add_u32_e32 v196, v242, v244
	v_add_u32_e32 v149, 0x10000, v148
	v_add_u32_e32 v197, 0x10000, v196
	v_add_u32_e32 v150, 0x20000, v148
	v_add_u32_e32 v224, 0x20000, v196
	v_add_u32_e32 v151, 0x30000, v148
	v_add_u32_e32 v225, 0x30000, v196
	v_add_u32_e32 v152, 0x80000, v148
	v_add_u32_e32 v226, 0x80000, v196
	v_add_u32_e32 v153, 0x90000, v148
	v_add_u32_e32 v227, 0x90000, v196
	v_add_u32_e32 v154, 0xa0000, v148
	v_add_u32_e32 v240, 0xa0000, v196
	v_add_u32_e32 v155, 0xb0000, v148
	v_add_u32_e32 v241, 0xb0000, v196
	global_load_dwordx4 v[160:163], v148, s[4:5]
	global_load_dwordx4 v[164:167], v196, s[4:5]
	global_load_dwordx4 v[168:171], v148, s[4:5] offset:512
	global_load_dwordx4 v[172:175], v196, s[4:5] offset:512
	global_load_dwordx4 v[176:179], v149, s[4:5]
	global_load_dwordx4 v[180:183], v197, s[4:5]
	global_load_dwordx4 v[184:187], v149, s[4:5] offset:512
	global_load_dwordx4 v[188:191], v197, s[4:5] offset:512
	global_load_dwordx4 v[192:195], v150, s[4:5]
	global_load_dwordx4 v[208:211], v224, s[4:5]
	global_load_dwordx4 v[212:215], v150, s[4:5] offset:512
	global_load_dwordx4 v[216:219], v224, s[4:5] offset:512
	global_load_dwordx4 v[220:223], v151, s[4:5]
	global_load_dwordx4 v[138:141], v225, s[4:5]
	global_load_dwordx4 v[134:137], v151, s[4:5] offset:512
	global_load_dwordx4 v[130:133], v225, s[4:5] offset:512
	v_mov_b32_dpp v122, v122 row_ror:8 row_mask:0xf bank_mask:0xf
	v_mov_b32_dpp v123, v123 row_ror:8 row_mask:0xf bank_mask:0xf
	v_mov_b32_dpp v124, v124 row_ror:8 row_mask:0xf bank_mask:0xf
	v_mov_b32_dpp v125, v125 row_ror:8 row_mask:0xf bank_mask:0xf
	v_mov_b32_dpp v110, v110 row_ror:8 row_mask:0xf bank_mask:0xf
	v_mov_b32_dpp v111, v111 row_ror:8 row_mask:0xf bank_mask:0xf
	v_mov_b32_dpp v112, v112 row_ror:8 row_mask:0xf bank_mask:0xf
	v_mov_b32_dpp v113, v113 row_ror:8 row_mask:0xf bank_mask:0xf
	v_mov_b32_dpp v106, v106 row_ror:8 row_mask:0xf bank_mask:0xf
	v_mov_b32_dpp v107, v107 row_ror:8 row_mask:0xf bank_mask:0xf
	v_mov_b32_dpp v108, v108 row_ror:8 row_mask:0xf bank_mask:0xf
	v_mov_b32_dpp v109, v109 row_ror:8 row_mask:0xf bank_mask:0xf
	v_mov_b32_dpp v94, v94 row_ror:8 row_mask:0xf bank_mask:0xf
	v_mov_b32_dpp v95, v95 row_ror:8 row_mask:0xf bank_mask:0xf
	v_mov_b32_dpp v96, v96 row_ror:8 row_mask:0xf bank_mask:0xf
	v_mov_b32_dpp v97, v97 row_ror:8 row_mask:0xf bank_mask:0xf
	v_mov_b32_dpp v90, v90 row_ror:8 row_mask:0xf bank_mask:0xf
	v_mov_b32_dpp v91, v91 row_ror:8 row_mask:0xf bank_mask:0xf
	v_mov_b32_dpp v92, v92 row_ror:8 row_mask:0xf bank_mask:0xf
	v_mov_b32_dpp v93, v93 row_ror:8 row_mask:0xf bank_mask:0xf
	v_mov_b32_dpp v78, v78 row_ror:8 row_mask:0xf bank_mask:0xf
	v_mov_b32_dpp v79, v79 row_ror:8 row_mask:0xf bank_mask:0xf
	v_mov_b32_dpp v80, v80 row_ror:8 row_mask:0xf bank_mask:0xf
	v_mov_b32_dpp v81, v81 row_ror:8 row_mask:0xf bank_mask:0xf
	v_mov_b32_dpp v74, v74 row_ror:8 row_mask:0xf bank_mask:0xf
	v_mov_b32_dpp v75, v75 row_ror:8 row_mask:0xf bank_mask:0xf
	v_mov_b32_dpp v76, v76 row_ror:8 row_mask:0xf bank_mask:0xf
	v_mov_b32_dpp v77, v77 row_ror:8 row_mask:0xf bank_mask:0xf
	v_mov_b32_dpp v66, v66 row_ror:8 row_mask:0xf bank_mask:0xf
	v_mov_b32_dpp v67, v67 row_ror:8 row_mask:0xf bank_mask:0xf
	v_mov_b32_dpp v68, v68 row_ror:8 row_mask:0xf bank_mask:0xf
	v_mov_b32_dpp v69, v69 row_ror:8 row_mask:0xf bank_mask:0xf
	s_mov_b32 exec_lo, 0xff00ff00
	s_mov_b32 exec_hi, 0xff00ff00
	v_swap_b32 v126, v122
	v_swap_b32 v127, v123
	v_swap_b32 v128, v124
	v_swap_b32 v129, v125
	v_swap_b32 v114, v110
	v_swap_b32 v115, v111
	v_swap_b32 v116, v112
	v_swap_b32 v117, v113
	v_swap_b32 v118, v106
	v_swap_b32 v119, v107
	v_swap_b32 v120, v108
	v_swap_b32 v121, v109
	v_swap_b32 v98, v94
	v_swap_b32 v99, v95
	v_swap_b32 v100, v96
	v_swap_b32 v101, v97
	v_swap_b32 v102, v90
	v_swap_b32 v103, v91
	v_swap_b32 v104, v92
	v_swap_b32 v105, v93
	v_swap_b32 v82, v78
	v_swap_b32 v83, v79
	v_swap_b32 v84, v80
	v_swap_b32 v85, v81
	v_swap_b32 v86, v74
	v_swap_b32 v87, v75
	v_swap_b32 v88, v76
	v_swap_b32 v89, v77
	v_swap_b32 v70, v66
	v_swap_b32 v71, v67
	v_swap_b32 v72, v68
	v_swap_b32 v73, v69
	s_mov_b64 exec, -1
	s_waitcnt vmcnt(12)
	v_pk_fma_f32 v[126:127], v[126:127], 0.5, v[160:161] op_sel_hi:[1,0,1]
	v_pk_fma_f32 v[128:129], v[128:129], 0.5, v[162:163] op_sel_hi:[1,0,1]
	v_pk_fma_f32 v[122:123], v[122:123], 0.5, v[164:165] op_sel_hi:[1,0,1]
	v_pk_fma_f32 v[124:125], v[124:125], 0.5, v[166:167] op_sel_hi:[1,0,1]
	v_pk_fma_f32 v[114:115], v[114:115], 0.5, v[168:169] op_sel_hi:[1,0,1]
	v_pk_fma_f32 v[116:117], v[116:117], 0.5, v[170:171] op_sel_hi:[1,0,1]
	v_pk_fma_f32 v[110:111], v[110:111], 0.5, v[172:173] op_sel_hi:[1,0,1]
	v_pk_fma_f32 v[112:113], v[112:113], 0.5, v[174:175] op_sel_hi:[1,0,1]
	s_waitcnt vmcnt(8)
	v_pk_fma_f32 v[118:119], v[118:119], 0.5, v[176:177] op_sel_hi:[1,0,1]
	v_pk_fma_f32 v[120:121], v[120:121], 0.5, v[178:179] op_sel_hi:[1,0,1]
	v_pk_fma_f32 v[106:107], v[106:107], 0.5, v[180:181] op_sel_hi:[1,0,1]
	v_pk_fma_f32 v[108:109], v[108:109], 0.5, v[182:183] op_sel_hi:[1,0,1]
	v_pk_fma_f32 v[98:99], v[98:99], 0.5, v[184:185] op_sel_hi:[1,0,1]
	v_pk_fma_f32 v[100:101], v[100:101], 0.5, v[186:187] op_sel_hi:[1,0,1]
	v_pk_fma_f32 v[94:95], v[94:95], 0.5, v[188:189] op_sel_hi:[1,0,1]
	v_pk_fma_f32 v[96:97], v[96:97], 0.5, v[190:191] op_sel_hi:[1,0,1]
	s_waitcnt vmcnt(4)
	v_pk_fma_f32 v[102:103], v[102:103], 0.5, v[192:193] op_sel_hi:[1,0,1]
	v_pk_fma_f32 v[104:105], v[104:105], 0.5, v[194:195] op_sel_hi:[1,0,1]
	v_pk_fma_f32 v[90:91], v[90:91], 0.5, v[208:209] op_sel_hi:[1,0,1]
	v_pk_fma_f32 v[92:93], v[92:93], 0.5, v[210:211] op_sel_hi:[1,0,1]
	v_pk_fma_f32 v[82:83], v[82:83], 0.5, v[212:213] op_sel_hi:[1,0,1]
	v_pk_fma_f32 v[84:85], v[84:85], 0.5, v[214:215] op_sel_hi:[1,0,1]
	v_pk_fma_f32 v[78:79], v[78:79], 0.5, v[216:217] op_sel_hi:[1,0,1]
	v_pk_fma_f32 v[80:81], v[80:81], 0.5, v[218:219] op_sel_hi:[1,0,1]
	s_waitcnt vmcnt(0)
	v_pk_fma_f32 v[86:87], v[86:87], 0.5, v[220:221] op_sel_hi:[1,0,1]
	v_pk_fma_f32 v[88:89], v[88:89], 0.5, v[222:223] op_sel_hi:[1,0,1]
	v_pk_fma_f32 v[74:75], v[74:75], 0.5, v[138:139] op_sel_hi:[1,0,1]
	v_pk_fma_f32 v[76:77], v[76:77], 0.5, v[140:141] op_sel_hi:[1,0,1]
	v_pk_fma_f32 v[70:71], v[70:71], 0.5, v[134:135] op_sel_hi:[1,0,1]
	v_pk_fma_f32 v[72:73], v[72:73], 0.5, v[136:137] op_sel_hi:[1,0,1]
	v_pk_fma_f32 v[66:67], v[66:67], 0.5, v[130:131] op_sel_hi:[1,0,1]
	v_pk_fma_f32 v[68:69], v[68:69], 0.5, v[132:133] op_sel_hi:[1,0,1]
	global_load_dwordx4 v[160:163], v152, s[4:5]
	global_load_dwordx4 v[164:167], v226, s[4:5]
	global_load_dwordx4 v[168:171], v152, s[4:5] offset:512
	global_load_dwordx4 v[172:175], v226, s[4:5] offset:512
	global_load_dwordx4 v[176:179], v153, s[4:5]
	global_load_dwordx4 v[180:183], v227, s[4:5]
	global_load_dwordx4 v[184:187], v153, s[4:5] offset:512
	global_load_dwordx4 v[188:191], v227, s[4:5] offset:512
	global_load_dwordx4 v[192:195], v154, s[4:5]
	global_load_dwordx4 v[208:211], v240, s[4:5]
	global_load_dwordx4 v[212:215], v154, s[4:5] offset:512
	global_load_dwordx4 v[216:219], v240, s[4:5] offset:512
	global_load_dwordx4 v[220:223], v155, s[4:5]
	global_load_dwordx4 v[138:141], v241, s[4:5]
	global_load_dwordx4 v[134:137], v155, s[4:5] offset:512
	global_load_dwordx4 v[130:133], v241, s[4:5] offset:512
	s_nop 4
	v_mov_b32_dpp v58, v58 row_ror:8 row_mask:0xf bank_mask:0xf
	v_mov_b32_dpp v59, v59 row_ror:8 row_mask:0xf bank_mask:0xf
	v_mov_b32_dpp v60, v60 row_ror:8 row_mask:0xf bank_mask:0xf
	v_mov_b32_dpp v61, v61 row_ror:8 row_mask:0xf bank_mask:0xf
	v_mov_b32_dpp v34, v34 row_ror:8 row_mask:0xf bank_mask:0xf
	v_mov_b32_dpp v35, v35 row_ror:8 row_mask:0xf bank_mask:0xf
	v_mov_b32_dpp v36, v36 row_ror:8 row_mask:0xf bank_mask:0xf
	v_mov_b32_dpp v37, v37 row_ror:8 row_mask:0xf bank_mask:0xf
	v_mov_b32_dpp v50, v50 row_ror:8 row_mask:0xf bank_mask:0xf
	v_mov_b32_dpp v51, v51 row_ror:8 row_mask:0xf bank_mask:0xf
	v_mov_b32_dpp v52, v52 row_ror:8 row_mask:0xf bank_mask:0xf
	v_mov_b32_dpp v53, v53 row_ror:8 row_mask:0xf bank_mask:0xf
	v_mov_b32_dpp v22, v22 row_ror:8 row_mask:0xf bank_mask:0xf
	v_mov_b32_dpp v23, v23 row_ror:8 row_mask:0xf bank_mask:0xf
	v_mov_b32_dpp v24, v24 row_ror:8 row_mask:0xf bank_mask:0xf
	v_mov_b32_dpp v25, v25 row_ror:8 row_mask:0xf bank_mask:0xf
	v_mov_b32_dpp v38, v38 row_ror:8 row_mask:0xf bank_mask:0xf
	v_mov_b32_dpp v39, v39 row_ror:8 row_mask:0xf bank_mask:0xf
	v_mov_b32_dpp v40, v40 row_ror:8 row_mask:0xf bank_mask:0xf
	v_mov_b32_dpp v41, v41 row_ror:8 row_mask:0xf bank_mask:0xf
	v_mov_b32_dpp v8, v8 row_ror:8 row_mask:0xf bank_mask:0xf
	v_mov_b32_dpp v9, v9 row_ror:8 row_mask:0xf bank_mask:0xf
	v_mov_b32_dpp v10, v10 row_ror:8 row_mask:0xf bank_mask:0xf
	v_mov_b32_dpp v11, v11 row_ror:8 row_mask:0xf bank_mask:0xf
	v_mov_b32_dpp v18, v18 row_ror:8 row_mask:0xf bank_mask:0xf
	v_mov_b32_dpp v19, v19 row_ror:8 row_mask:0xf bank_mask:0xf
	v_mov_b32_dpp v20, v20 row_ror:8 row_mask:0xf bank_mask:0xf
	v_mov_b32_dpp v21, v21 row_ror:8 row_mask:0xf bank_mask:0xf
	v_mov_b32_dpp v0, v0 row_ror:8 row_mask:0xf bank_mask:0xf
	v_mov_b32_dpp v1, v1 row_ror:8 row_mask:0xf bank_mask:0xf
	v_mov_b32_dpp v2, v2 row_ror:8 row_mask:0xf bank_mask:0xf
	v_mov_b32_dpp v3, v3 row_ror:8 row_mask:0xf bank_mask:0xf
	s_mov_b32 exec_lo, 0xff00ff00
	s_mov_b32 exec_hi, 0xff00ff00
	v_swap_b32 v62, v58
	v_swap_b32 v63, v59
	v_swap_b32 v64, v60
	v_swap_b32 v65, v61
	v_swap_b32 v42, v34
	v_swap_b32 v43, v35
	v_swap_b32 v44, v36
	v_swap_b32 v45, v37
	v_swap_b32 v54, v50
	v_swap_b32 v55, v51
	v_swap_b32 v56, v52
	v_swap_b32 v57, v53
	v_swap_b32 v26, v22
	v_swap_b32 v27, v23
	v_swap_b32 v28, v24
	v_swap_b32 v29, v25
	v_swap_b32 v46, v38
	v_swap_b32 v47, v39
	v_swap_b32 v48, v40
	v_swap_b32 v49, v41
	v_swap_b32 v12, v8
	v_swap_b32 v13, v9
	v_swap_b32 v14, v10
	v_swap_b32 v15, v11
	v_swap_b32 v30, v18
	v_swap_b32 v31, v19
	v_swap_b32 v32, v20
	v_swap_b32 v33, v21
	v_swap_b32 v4, v0
	v_swap_b32 v5, v1
	v_swap_b32 v6, v2
	v_swap_b32 v7, v3
	s_mov_b64 exec, -1
	global_store_dwordx4 v148, v[126:129], s[14:15]
	global_store_dwordx4 v196, v[122:125], s[14:15]
	global_store_dwordx4 v148, v[114:117], s[14:15] offset:512
	global_store_dwordx4 v196, v[110:113], s[14:15] offset:512
	global_store_dwordx4 v149, v[118:121], s[14:15]
	global_store_dwordx4 v197, v[106:109], s[14:15]
	global_store_dwordx4 v149, v[98:101], s[14:15] offset:512
	global_store_dwordx4 v197, v[94:97], s[14:15] offset:512
	global_store_dwordx4 v150, v[102:105], s[14:15]
	global_store_dwordx4 v224, v[90:93], s[14:15]
	global_store_dwordx4 v150, v[82:85], s[14:15] offset:512
	global_store_dwordx4 v224, v[78:81], s[14:15] offset:512
	global_store_dwordx4 v151, v[86:89], s[14:15]
	global_store_dwordx4 v225, v[74:77], s[14:15]
	global_store_dwordx4 v151, v[70:73], s[14:15] offset:512
	global_store_dwordx4 v225, v[66:69], s[14:15] offset:512
	s_waitcnt vmcnt(0)
	v_pk_fma_f32 v[62:63], v[62:63], 0.5, v[160:161] op_sel_hi:[1,0,1]
	v_pk_fma_f32 v[64:65], v[64:65], 0.5, v[162:163] op_sel_hi:[1,0,1]
	v_pk_fma_f32 v[58:59], v[58:59], 0.5, v[164:165] op_sel_hi:[1,0,1]
	v_pk_fma_f32 v[60:61], v[60:61], 0.5, v[166:167] op_sel_hi:[1,0,1]
	v_pk_fma_f32 v[42:43], v[42:43], 0.5, v[168:169] op_sel_hi:[1,0,1]
	v_pk_fma_f32 v[44:45], v[44:45], 0.5, v[170:171] op_sel_hi:[1,0,1]
	v_pk_fma_f32 v[34:35], v[34:35], 0.5, v[172:173] op_sel_hi:[1,0,1]
	v_pk_fma_f32 v[36:37], v[36:37], 0.5, v[174:175] op_sel_hi:[1,0,1]
	v_pk_fma_f32 v[54:55], v[54:55], 0.5, v[176:177] op_sel_hi:[1,0,1]
	v_pk_fma_f32 v[56:57], v[56:57], 0.5, v[178:179] op_sel_hi:[1,0,1]
	v_pk_fma_f32 v[50:51], v[50:51], 0.5, v[180:181] op_sel_hi:[1,0,1]
	v_pk_fma_f32 v[52:53], v[52:53], 0.5, v[182:183] op_sel_hi:[1,0,1]
	v_pk_fma_f32 v[26:27], v[26:27], 0.5, v[184:185] op_sel_hi:[1,0,1]
	v_pk_fma_f32 v[28:29], v[28:29], 0.5, v[186:187] op_sel_hi:[1,0,1]
	v_pk_fma_f32 v[22:23], v[22:23], 0.5, v[188:189] op_sel_hi:[1,0,1]
	v_pk_fma_f32 v[24:25], v[24:25], 0.5, v[190:191] op_sel_hi:[1,0,1]
	v_pk_fma_f32 v[46:47], v[46:47], 0.5, v[192:193] op_sel_hi:[1,0,1]
	v_pk_fma_f32 v[48:49], v[48:49], 0.5, v[194:195] op_sel_hi:[1,0,1]
	v_pk_fma_f32 v[38:39], v[38:39], 0.5, v[208:209] op_sel_hi:[1,0,1]
	v_pk_fma_f32 v[40:41], v[40:41], 0.5, v[210:211] op_sel_hi:[1,0,1]
	v_pk_fma_f32 v[12:13], v[12:13], 0.5, v[212:213] op_sel_hi:[1,0,1]
	v_pk_fma_f32 v[14:15], v[14:15], 0.5, v[214:215] op_sel_hi:[1,0,1]
	v_pk_fma_f32 v[8:9], v[8:9], 0.5, v[216:217] op_sel_hi:[1,0,1]
	v_pk_fma_f32 v[10:11], v[10:11], 0.5, v[218:219] op_sel_hi:[1,0,1]
	v_pk_fma_f32 v[30:31], v[30:31], 0.5, v[220:221] op_sel_hi:[1,0,1]
	v_pk_fma_f32 v[32:33], v[32:33], 0.5, v[222:223] op_sel_hi:[1,0,1]
	v_pk_fma_f32 v[18:19], v[18:19], 0.5, v[138:139] op_sel_hi:[1,0,1]
	v_pk_fma_f32 v[20:21], v[20:21], 0.5, v[140:141] op_sel_hi:[1,0,1]
	v_pk_fma_f32 v[4:5], v[4:5], 0.5, v[134:135] op_sel_hi:[1,0,1]
	v_pk_fma_f32 v[6:7], v[6:7], 0.5, v[136:137] op_sel_hi:[1,0,1]
	v_pk_fma_f32 v[0:1], v[0:1], 0.5, v[130:131] op_sel_hi:[1,0,1]
	v_pk_fma_f32 v[2:3], v[2:3], 0.5, v[132:133] op_sel_hi:[1,0,1]
	global_store_dwordx4 v152, v[62:65], s[14:15]
	global_store_dwordx4 v226, v[58:61], s[14:15]
	global_store_dwordx4 v152, v[42:45], s[14:15] offset:512
	global_store_dwordx4 v226, v[34:37], s[14:15] offset:512
	global_store_dwordx4 v153, v[54:57], s[14:15]
	global_store_dwordx4 v227, v[50:53], s[14:15]
	global_store_dwordx4 v153, v[26:29], s[14:15] offset:512
	global_store_dwordx4 v227, v[22:25], s[14:15] offset:512
	global_store_dwordx4 v154, v[46:49], s[14:15]
	global_store_dwordx4 v240, v[38:41], s[14:15]
	global_store_dwordx4 v154, v[12:15], s[14:15] offset:512
	global_store_dwordx4 v240, v[8:11], s[14:15] offset:512
	global_store_dwordx4 v155, v[30:33], s[14:15]
	global_store_dwordx4 v241, v[18:21], s[14:15]
	global_store_dwordx4 v155, v[4:7], s[14:15] offset:512
	global_store_dwordx4 v241, v[0:3], s[14:15] offset:512
	s_and_b64 vcc, exec, s[38:39]
	s_mov_b32 s12, s82
	s_mov_b32 s2, s83
	s_mov_b64 s[28:29], s[18:19]
	s_mov_b64 s[22:23], s[16:17]
	s_mov_b32 s86, 0x38c0000
	s_cbranch_vccz .LBB0_122
	s_waitcnt vmcnt(0)
	s_cmpk_gt_u32 s48, 0xff
	s_cbranch_scc1 .LBB0_137
	s_barrier

.LBB0_174:
	s_add_u32 s40, s22, 0x100
	s_addc_u32 s41, s23, 0
	s_add_i32 s83, 0, 0x10000
	v_add_u32_e32 v148, s83, v157
	ds_read_b128 v[130:133], v148
	ds_read_b128 v[134:137], v148 offset:1024
	ds_read_b128 v[138:141], v148 offset:2048
	ds_read_b128 v[148:151], v148 offset:3072
	s_cmp_eq_u32 s82, 12
	s_cselect_b32 s49, s9, s41
	s_cselect_b32 s48, s12, s40
	s_cselect_b32 s43, s5, s79
	s_cselect_b32 s42, s34, s61
	v_lshl_add_u64 v[188:189], s[22:23], 0, v[146:147]
	s_add_i32 m0, s19, 0xc000
	ds_read_b128 v[152:155], v159
	ds_read_b128 v[160:163], v159 offset:1024
	ds_read_b128 v[164:167], v159 offset:2048
	ds_read_b128 v[168:171], v159 offset:3072
	ds_read_b128 v[172:175], v159 offset:4096
	ds_read_b128 v[176:179], v159 offset:5120
	ds_read_b128 v[180:183], v159 offset:6144
	ds_read_b128 v[184:187], v159 offset:7168
	global_load_lds_dwordx4 v[188:189], off
	v_lshl_add_u64 v[188:189], s[22:23], 0, v[144:145]
	s_add_i32 m0, s19, 0xe000
	s_nop 0
	global_load_lds_dwordx4 v[188:189], off
	s_waitcnt lgkmcnt(8)
	s_waitcnt vmcnt(10)
	s_barrier
	s_waitcnt lgkmcnt(0)
	s_waitcnt lgkmcnt(0)
	v_mfma_f32_16x16x32_bf16 v[126:129], v[130:133], v[152:155], v[126:129]
	v_mfma_f32_16x16x32_bf16 v[122:125], v[138:141], v[152:155], v[122:125]
	v_mfma_f32_16x16x32_bf16 v[118:121], v[130:133], v[164:167], v[118:121]
	v_mfma_f32_16x16x32_bf16 v[106:109], v[138:141], v[164:167], v[106:109]
	v_mfma_f32_16x16x32_bf16 v[102:105], v[130:133], v[172:175], v[102:105]
	v_mfma_f32_16x16x32_bf16 v[90:93], v[138:141], v[172:175], v[90:93]
	v_mfma_f32_16x16x32_bf16 v[86:89], v[130:133], v[180:183], v[86:89]
	v_mfma_f32_16x16x32_bf16 v[74:77], v[138:141], v[180:183], v[74:77]
	v_mfma_f32_16x16x32_bf16 v[126:129], v[134:137], v[160:163], v[126:129]
	v_mfma_f32_16x16x32_bf16 v[122:125], v[148:151], v[160:163], v[122:125]
	v_mfma_f32_16x16x32_bf16 v[118:121], v[134:137], v[168:171], v[118:121]
	v_mfma_f32_16x16x32_bf16 v[106:109], v[148:151], v[168:171], v[106:109]
	v_mfma_f32_16x16x32_bf16 v[102:105], v[134:137], v[176:179], v[102:105]
	v_mfma_f32_16x16x32_bf16 v[90:93], v[148:151], v[176:179], v[90:93]
	v_mfma_f32_16x16x32_bf16 v[86:89], v[134:137], v[184:187], v[86:89]
	v_mfma_f32_16x16x32_bf16 v[74:77], v[148:151], v[184:187], v[74:77]
	s_barrier
	s_add_i32 s84, 0, 0x14000
	v_add_u32_e32 v196, s84, v157
	s_add_i32 s22, s83, s52
	ds_read_b128 v[188:191], v196
	ds_read_b128 v[192:195], v196 offset:1024
	ds_read_b128 v[208:211], v196 offset:2048
	ds_read_b128 v[212:215], v196 offset:3072
	v_lshl_add_u64 v[196:197], s[42:43], 0, v[16:17]
	s_mov_b32 m0, s22
	v_lshl_add_u64 v[216:217], s[42:43], 0, v[142:143]
	global_load_lds_dwordx4 v[196:197], off
	s_add_i32 m0, s22, 0x2000
	s_nop 0
	global_load_lds_dwordx4 v[216:217], off
	s_waitcnt vmcnt(10)
	s_barrier
	s_waitcnt lgkmcnt(0)
	s_waitcnt lgkmcnt(0)
	v_mfma_f32_16x16x32_bf16 v[114:117], v[188:191], v[152:155], v[114:117]
	v_mfma_f32_16x16x32_bf16 v[110:113], v[208:211], v[152:155], v[110:113]
	v_mfma_f32_16x16x32_bf16 v[98:101], v[188:191], v[164:167], v[98:101]
	v_mfma_f32_16x16x32_bf16 v[94:97], v[208:211], v[164:167], v[94:97]
	v_mfma_f32_16x16x32_bf16 v[82:85], v[188:191], v[172:175], v[82:85]
	v_mfma_f32_16x16x32_bf16 v[78:81], v[208:211], v[172:175], v[78:81]
	v_mfma_f32_16x16x32_bf16 v[70:73], v[188:191], v[180:183], v[70:73]
	v_mfma_f32_16x16x32_bf16 v[66:69], v[208:211], v[180:183], v[66:69]
	v_mfma_f32_16x16x32_bf16 v[114:117], v[192:195], v[160:163], v[114:117]
	v_mfma_f32_16x16x32_bf16 v[110:113], v[212:215], v[160:163], v[110:113]
	v_mfma_f32_16x16x32_bf16 v[98:101], v[192:195], v[168:171], v[98:101]
	v_mfma_f32_16x16x32_bf16 v[94:97], v[212:215], v[168:171], v[94:97]
	v_mfma_f32_16x16x32_bf16 v[82:85], v[192:195], v[176:179], v[82:85]
	v_mfma_f32_16x16x32_bf16 v[78:81], v[212:215], v[176:179], v[78:81]
	v_mfma_f32_16x16x32_bf16 v[70:73], v[192:195], v[184:187], v[70:73]
	v_mfma_f32_16x16x32_bf16 v[66:69], v[212:215], v[184:187], v[66:69]
	s_mov_b32 m0, s19
	v_lshl_add_u64 v[218:219], s[48:49], 0, v[16:17]
	s_barrier
	ds_read_b128 v[152:155], v159 offset:16384
	ds_read_b128 v[160:163], v159 offset:17408
	ds_read_b128 v[164:167], v159 offset:18432
	ds_read_b128 v[168:171], v159 offset:19456
	ds_read_b128 v[172:175], v159 offset:20480
	ds_read_b128 v[176:179], v159 offset:21504
	ds_read_b128 v[180:183], v159 offset:22528
	ds_read_b128 v[184:187], v159 offset:23552
	global_load_lds_dwordx4 v[218:219], off
	v_lshl_add_u64 v[220:221], s[48:49], 0, v[142:143]
	s_mov_b32 m0, s54
	s_nop 0
	global_load_lds_dwordx4 v[220:221], off
	s_barrier
	s_waitcnt lgkmcnt(0)
	s_waitcnt lgkmcnt(0)
	v_mfma_f32_16x16x32_bf16 v[62:65], v[130:133], v[152:155], v[62:65]
	v_mfma_f32_16x16x32_bf16 v[58:61], v[138:141], v[152:155], v[58:61]
	v_mfma_f32_16x16x32_bf16 v[54:57], v[130:133], v[164:167], v[54:57]
	v_mfma_f32_16x16x32_bf16 v[50:53], v[138:141], v[164:167], v[50:53]
	v_mfma_f32_16x16x32_bf16 v[46:49], v[130:133], v[172:175], v[46:49]
	v_mfma_f32_16x16x32_bf16 v[38:41], v[138:141], v[172:175], v[38:41]
	v_mfma_f32_16x16x32_bf16 v[30:33], v[130:133], v[180:183], v[30:33]
	v_mfma_f32_16x16x32_bf16 v[18:21], v[138:141], v[180:183], v[18:21]
	v_mfma_f32_16x16x32_bf16 v[62:65], v[134:137], v[160:163], v[62:65]
	v_mfma_f32_16x16x32_bf16 v[58:61], v[148:151], v[160:163], v[58:61]
	v_mfma_f32_16x16x32_bf16 v[54:57], v[134:137], v[168:171], v[54:57]
	v_mfma_f32_16x16x32_bf16 v[50:53], v[148:151], v[168:171], v[50:53]
	v_mfma_f32_16x16x32_bf16 v[46:49], v[134:137], v[176:179], v[46:49]
	v_mfma_f32_16x16x32_bf16 v[38:41], v[148:151], v[176:179], v[38:41]
	v_mfma_f32_16x16x32_bf16 v[30:33], v[134:137], v[184:187], v[30:33]
	v_mfma_f32_16x16x32_bf16 v[18:21], v[148:151], v[184:187], v[18:21]
	s_barrier
	s_add_u32 s22, s42, 0x40000
	s_addc_u32 s23, s43, 0
	s_add_i32 s83, s84, s52
	v_lshl_add_u64 v[130:131], s[22:23], 0, v[16:17]
	s_mov_b32 m0, s83
	s_nop 0
	global_load_lds_dwordx4 v[130:131], off
	v_lshl_add_u64 v[130:131], s[22:23], 0, v[142:143]
	s_add_i32 m0, s83, 0x2000
	s_nop 0
	global_load_lds_dwordx4 v[130:131], off
	s_waitcnt vmcnt(10)
	s_barrier
	v_mfma_f32_16x16x32_bf16 v[42:45], v[188:191], v[152:155], v[42:45]
	v_mfma_f32_16x16x32_bf16 v[34:37], v[208:211], v[152:155], v[34:37]
	v_mfma_f32_16x16x32_bf16 v[26:29], v[188:191], v[164:167], v[26:29]
	v_mfma_f32_16x16x32_bf16 v[22:25], v[208:211], v[164:167], v[22:25]
	v_mfma_f32_16x16x32_bf16 v[12:15], v[188:191], v[172:175], v[12:15]
	v_mfma_f32_16x16x32_bf16 v[8:11], v[208:211], v[172:175], v[8:11]
	v_mfma_f32_16x16x32_bf16 v[4:7], v[188:191], v[180:183], v[4:7]
	v_mfma_f32_16x16x32_bf16 v[0:3], v[208:211], v[180:183], v[0:3]
	v_mfma_f32_16x16x32_bf16 v[42:45], v[192:195], v[160:163], v[42:45]
	v_mfma_f32_16x16x32_bf16 v[34:37], v[212:215], v[160:163], v[34:37]
	v_mfma_f32_16x16x32_bf16 v[26:29], v[192:195], v[168:171], v[26:29]
	v_mfma_f32_16x16x32_bf16 v[22:25], v[212:215], v[168:171], v[22:25]
	v_mfma_f32_16x16x32_bf16 v[12:15], v[192:195], v[176:179], v[12:15]
	v_mfma_f32_16x16x32_bf16 v[8:11], v[212:215], v[176:179], v[8:11]
	v_mfma_f32_16x16x32_bf16 v[4:7], v[192:195], v[184:187], v[4:7]
	v_mfma_f32_16x16x32_bf16 v[0:3], v[212:215], v[184:187], v[0:3]
	s_add_i32 s83, 0, 0x18000
	v_add_u32_e32 v148, s83, v157
	s_barrier
	ds_read_b128 v[130:133], v148
	ds_read_b128 v[134:137], v148 offset:1024
	ds_read_b128 v[138:141], v148 offset:2048
	ds_read_b128 v[148:151], v148 offset:3072
	s_add_u32 s22, s48, 0x40000
	s_addc_u32 s23, s49, 0
	s_mov_b32 m0, s55
	v_lshl_add_u64 v[188:189], s[22:23], 0, v[16:17]
	ds_read_b128 v[152:155], v159 offset:32768
	ds_read_b128 v[160:163], v159 offset:33792
	ds_read_b128 v[164:167], v159 offset:34816
	ds_read_b128 v[168:171], v159 offset:35840
	ds_read_b128 v[172:175], v159 offset:36864
	ds_read_b128 v[176:179], v159 offset:37888
	ds_read_b128 v[180:183], v159 offset:38912
	ds_read_b128 v[184:187], v159 offset:39936
	global_load_lds_dwordx4 v[188:189], off
	v_lshl_add_u64 v[188:189], s[22:23], 0, v[142:143]
	s_mov_b32 m0, s56
	s_nop 0
	global_load_lds_dwordx4 v[188:189], off
	s_waitcnt lgkmcnt(8)
	s_waitcnt vmcnt(10)
	s_barrier
	s_waitcnt lgkmcnt(0)
	s_waitcnt lgkmcnt(0)
	v_mfma_f32_16x16x32_bf16 v[126:129], v[130:133], v[152:155], v[126:129]
	v_mfma_f32_16x16x32_bf16 v[122:125], v[138:141], v[152:155], v[122:125]
	v_mfma_f32_16x16x32_bf16 v[118:121], v[130:133], v[164:167], v[118:121]
	v_mfma_f32_16x16x32_bf16 v[106:109], v[138:141], v[164:167], v[106:109]
	v_mfma_f32_16x16x32_bf16 v[102:105], v[130:133], v[172:175], v[102:105]
	v_mfma_f32_16x16x32_bf16 v[90:93], v[138:141], v[172:175], v[90:93]
	v_mfma_f32_16x16x32_bf16 v[86:89], v[130:133], v[180:183], v[86:89]
	v_mfma_f32_16x16x32_bf16 v[74:77], v[138:141], v[180:183], v[74:77]
	v_mfma_f32_16x16x32_bf16 v[126:129], v[134:137], v[160:163], v[126:129]
	v_mfma_f32_16x16x32_bf16 v[122:125], v[148:151], v[160:163], v[122:125]
	v_mfma_f32_16x16x32_bf16 v[118:121], v[134:137], v[168:171], v[118:121]
	v_mfma_f32_16x16x32_bf16 v[106:109], v[148:151], v[168:171], v[106:109]
	v_mfma_f32_16x16x32_bf16 v[102:105], v[134:137], v[176:179], v[102:105]
	v_mfma_f32_16x16x32_bf16 v[90:93], v[148:151], v[176:179], v[90:93]
	v_mfma_f32_16x16x32_bf16 v[86:89], v[134:137], v[184:187], v[86:89]
	v_mfma_f32_16x16x32_bf16 v[74:77], v[148:151], v[184:187], v[74:77]
	s_barrier
	s_add_i32 s48, 0, 0x1c000
	s_add_i32 s22, s83, s52
	v_add_u32_e32 v212, s48, v157
	v_lshl_add_u64 v[196:197], v[196:197], 0, s[10:11]
	s_mov_b32 m0, s22
	ds_read_b128 v[188:191], v212
	ds_read_b128 v[192:195], v212 offset:1024
	ds_read_b128 v[208:211], v212 offset:2048
	ds_read_b128 v[212:215], v212 offset:3072
	global_load_lds_dwordx4 v[196:197], off
	v_lshl_add_u64 v[196:197], v[216:217], 0, s[10:11]
	s_add_i32 m0, s22, 0x2000
	s_nop 0
	global_load_lds_dwordx4 v[196:197], off
	s_waitcnt vmcnt(10)
	s_barrier
	s_waitcnt lgkmcnt(0)
	s_waitcnt lgkmcnt(0)
	v_mfma_f32_16x16x32_bf16 v[114:117], v[188:191], v[152:155], v[114:117]
	v_mfma_f32_16x16x32_bf16 v[110:113], v[208:211], v[152:155], v[110:113]
	v_mfma_f32_16x16x32_bf16 v[98:101], v[188:191], v[164:167], v[98:101]
	v_mfma_f32_16x16x32_bf16 v[94:97], v[208:211], v[164:167], v[94:97]
	v_mfma_f32_16x16x32_bf16 v[82:85], v[188:191], v[172:175], v[82:85]
	v_mfma_f32_16x16x32_bf16 v[78:81], v[208:211], v[172:175], v[78:81]
	v_mfma_f32_16x16x32_bf16 v[70:73], v[188:191], v[180:183], v[70:73]
	v_mfma_f32_16x16x32_bf16 v[66:69], v[208:211], v[180:183], v[66:69]
	v_mfma_f32_16x16x32_bf16 v[114:117], v[192:195], v[160:163], v[114:117]
	v_mfma_f32_16x16x32_bf16 v[110:113], v[212:215], v[160:163], v[110:113]
	v_mfma_f32_16x16x32_bf16 v[98:101], v[192:195], v[168:171], v[98:101]
	v_mfma_f32_16x16x32_bf16 v[94:97], v[212:215], v[168:171], v[94:97]
	v_mfma_f32_16x16x32_bf16 v[82:85], v[192:195], v[176:179], v[82:85]
	v_mfma_f32_16x16x32_bf16 v[78:81], v[212:215], v[176:179], v[78:81]
	v_mfma_f32_16x16x32_bf16 v[70:73], v[192:195], v[184:187], v[70:73]
	v_mfma_f32_16x16x32_bf16 v[66:69], v[212:215], v[184:187], v[66:69]
	s_mov_b32 m0, s57
	v_lshl_add_u64 v[196:197], v[218:219], 0, s[10:11]
	s_barrier
	ds_read_b128 v[152:155], v159 offset:49152
	ds_read_b128 v[160:163], v159 offset:50176
	ds_read_b128 v[164:167], v159 offset:51200
	ds_read_b128 v[168:171], v159 offset:52224
	ds_read_b128 v[172:175], v159 offset:53248
	ds_read_b128 v[176:179], v159 offset:54272
	ds_read_b128 v[180:183], v159 offset:55296
	ds_read_b128 v[184:187], v159 offset:56320
	global_load_lds_dwordx4 v[196:197], off
	v_lshl_add_u64 v[196:197], v[220:221], 0, s[10:11]
	s_mov_b32 m0, s58
	s_nop 0
	global_load_lds_dwordx4 v[196:197], off
	s_barrier
	s_waitcnt lgkmcnt(0)
	s_waitcnt lgkmcnt(0)
	v_mfma_f32_16x16x32_bf16 v[62:65], v[130:133], v[152:155], v[62:65]
	v_mfma_f32_16x16x32_bf16 v[58:61], v[138:141], v[152:155], v[58:61]
	v_mfma_f32_16x16x32_bf16 v[54:57], v[130:133], v[164:167], v[54:57]
	v_mfma_f32_16x16x32_bf16 v[50:53], v[138:141], v[164:167], v[50:53]
	v_mfma_f32_16x16x32_bf16 v[46:49], v[130:133], v[172:175], v[46:49]
	v_mfma_f32_16x16x32_bf16 v[38:41], v[138:141], v[172:175], v[38:41]
	v_mfma_f32_16x16x32_bf16 v[30:33], v[130:133], v[180:183], v[30:33]
	v_mfma_f32_16x16x32_bf16 v[18:21], v[138:141], v[180:183], v[18:21]
	v_mfma_f32_16x16x32_bf16 v[62:65], v[134:137], v[160:163], v[62:65]
	v_mfma_f32_16x16x32_bf16 v[58:61], v[148:151], v[160:163], v[58:61]
	v_mfma_f32_16x16x32_bf16 v[54:57], v[134:137], v[168:171], v[54:57]
	v_mfma_f32_16x16x32_bf16 v[50:53], v[148:151], v[168:171], v[50:53]
	v_mfma_f32_16x16x32_bf16 v[46:49], v[134:137], v[176:179], v[46:49]
	v_mfma_f32_16x16x32_bf16 v[38:41], v[148:151], v[176:179], v[38:41]
	v_mfma_f32_16x16x32_bf16 v[30:33], v[134:137], v[184:187], v[30:33]
	v_mfma_f32_16x16x32_bf16 v[18:21], v[148:151], v[184:187], v[18:21]
	s_barrier
	s_add_u32 s22, s42, 0x40080
	s_addc_u32 s23, s43, 0
	s_add_i32 s42, s48, s52
	v_lshl_add_u64 v[130:131], s[22:23], 0, v[16:17]
	s_mov_b32 m0, s42
	s_nop 0
	global_load_lds_dwordx4 v[130:131], off
	v_lshl_add_u64 v[130:131], s[22:23], 0, v[142:143]
	s_add_i32 m0, s42, 0x2000
	s_nop 0
	global_load_lds_dwordx4 v[130:131], off
	s_waitcnt vmcnt(10)
	s_barrier
	v_mfma_f32_16x16x32_bf16 v[42:45], v[188:191], v[152:155], v[42:45]
	v_mfma_f32_16x16x32_bf16 v[34:37], v[208:211], v[152:155], v[34:37]
	v_mfma_f32_16x16x32_bf16 v[26:29], v[188:191], v[164:167], v[26:29]
	v_mfma_f32_16x16x32_bf16 v[22:25], v[208:211], v[164:167], v[22:25]
	v_mfma_f32_16x16x32_bf16 v[12:15], v[188:191], v[172:175], v[12:15]
	v_mfma_f32_16x16x32_bf16 v[8:11], v[208:211], v[172:175], v[8:11]
	v_mfma_f32_16x16x32_bf16 v[4:7], v[188:191], v[180:183], v[4:7]
	v_mfma_f32_16x16x32_bf16 v[0:3], v[208:211], v[180:183], v[0:3]
	v_mfma_f32_16x16x32_bf16 v[42:45], v[192:195], v[160:163], v[42:45]
	v_mfma_f32_16x16x32_bf16 v[34:37], v[212:215], v[160:163], v[34:37]
	v_mfma_f32_16x16x32_bf16 v[26:29], v[192:195], v[168:171], v[26:29]
	v_mfma_f32_16x16x32_bf16 v[22:25], v[212:215], v[168:171], v[22:25]
	v_mfma_f32_16x16x32_bf16 v[12:15], v[192:195], v[176:179], v[12:15]
	v_mfma_f32_16x16x32_bf16 v[8:11], v[212:215], v[176:179], v[8:11]
	v_mfma_f32_16x16x32_bf16 v[4:7], v[192:195], v[184:187], v[4:7]
	v_mfma_f32_16x16x32_bf16 v[0:3], v[212:215], v[184:187], v[0:3]
	s_add_i32 s82, s82, 2
	s_add_u32 s61, s61, 0x100
	s_addc_u32 s79, s79, 0
	s_cmp_gt_u32 s82, 13
	s_mov_b64 s[22:23], s[40:41]
	s_barrier
	s_cbranch_scc0 .LBB0_174
	v_lshl_or_b32 v242, s2, 8, v158
	v_lshl_add_u32 v243, s18, 8, v156
	v_lshlrev_b32_e32 v242, 2, v242
	v_lshl_add_u32 v242, v243, 12, v242
	v_and_b32_e32 v243, 8, v156
	v_mul_u32_u24_e32 v244, 0xff8, v243
	v_sub_u32_e32 v148, v242, v244
	v_sub_u32_e32 v243, 8, v243
	v_mul_u32_u24_e32 v244, 0x1008, v243
	v_add_u32_e32 v196, v242, v244
	v_add_u32_e32 v149, 0x10000, v148
	v_add_u32_e32 v197, 0x10000, v196
	v_add_u32_e32 v150, 0x20000, v148
	v_add_u32_e32 v224, 0x20000, v196
	v_add_u32_e32 v151, 0x30000, v148
	v_add_u32_e32 v225, 0x30000, v196
	v_add_u32_e32 v152, 0x80000, v148
	v_add_u32_e32 v226, 0x80000, v196
	v_add_u32_e32 v153, 0x90000, v148
	v_add_u32_e32 v227, 0x90000, v196
	v_add_u32_e32 v154, 0xa0000, v148
	v_add_u32_e32 v240, 0xa0000, v196
	v_add_u32_e32 v155, 0xb0000, v148
	v_add_u32_e32 v241, 0xb0000, v196
	global_load_dwordx4 v[160:163], v148, s[20:21]
	global_load_dwordx4 v[164:167], v196, s[20:21]
	global_load_dwordx4 v[168:171], v148, s[20:21] offset:512
	global_load_dwordx4 v[172:175], v196, s[20:21] offset:512
	global_load_dwordx4 v[176:179], v149, s[20:21]
	global_load_dwordx4 v[180:183], v197, s[20:21]
	global_load_dwordx4 v[184:187], v149, s[20:21] offset:512
	global_load_dwordx4 v[188:191], v197, s[20:21] offset:512
	global_load_dwordx4 v[192:195], v150, s[20:21]
	global_load_dwordx4 v[208:211], v224, s[20:21]
	global_load_dwordx4 v[212:215], v150, s[20:21] offset:512
	global_load_dwordx4 v[216:219], v224, s[20:21] offset:512
	global_load_dwordx4 v[220:223], v151, s[20:21]
	global_load_dwordx4 v[138:141], v225, s[20:21]
	global_load_dwordx4 v[134:137], v151, s[20:21] offset:512
	global_load_dwordx4 v[130:133], v225, s[20:21] offset:512
	v_mov_b32_dpp v122, v122 row_ror:8 row_mask:0xf bank_mask:0xf
	v_mov_b32_dpp v123, v123 row_ror:8 row_mask:0xf bank_mask:0xf
	v_mov_b32_dpp v124, v124 row_ror:8 row_mask:0xf bank_mask:0xf
	v_mov_b32_dpp v125, v125 row_ror:8 row_mask:0xf bank_mask:0xf
	v_mov_b32_dpp v110, v110 row_ror:8 row_mask:0xf bank_mask:0xf
	v_mov_b32_dpp v111, v111 row_ror:8 row_mask:0xf bank_mask:0xf
	v_mov_b32_dpp v112, v112 row_ror:8 row_mask:0xf bank_mask:0xf
	v_mov_b32_dpp v113, v113 row_ror:8 row_mask:0xf bank_mask:0xf
	v_mov_b32_dpp v106, v106 row_ror:8 row_mask:0xf bank_mask:0xf
	v_mov_b32_dpp v107, v107 row_ror:8 row_mask:0xf bank_mask:0xf
	v_mov_b32_dpp v108, v108 row_ror:8 row_mask:0xf bank_mask:0xf
	v_mov_b32_dpp v109, v109 row_ror:8 row_mask:0xf bank_mask:0xf
	v_mov_b32_dpp v94, v94 row_ror:8 row_mask:0xf bank_mask:0xf
	v_mov_b32_dpp v95, v95 row_ror:8 row_mask:0xf bank_mask:0xf
	v_mov_b32_dpp v96, v96 row_ror:8 row_mask:0xf bank_mask:0xf
	v_mov_b32_dpp v97, v97 row_ror:8 row_mask:0xf bank_mask:0xf
	v_mov_b32_dpp v90, v90 row_ror:8 row_mask:0xf bank_mask:0xf
	v_mov_b32_dpp v91, v91 row_ror:8 row_mask:0xf bank_mask:0xf
	v_mov_b32_dpp v92, v92 row_ror:8 row_mask:0xf bank_mask:0xf
	v_mov_b32_dpp v93, v93 row_ror:8 row_mask:0xf bank_mask:0xf
	v_mov_b32_dpp v78, v78 row_ror:8 row_mask:0xf bank_mask:0xf
	v_mov_b32_dpp v79, v79 row_ror:8 row_mask:0xf bank_mask:0xf
	v_mov_b32_dpp v80, v80 row_ror:8 row_mask:0xf bank_mask:0xf
	v_mov_b32_dpp v81, v81 row_ror:8 row_mask:0xf bank_mask:0xf
	v_mov_b32_dpp v74, v74 row_ror:8 row_mask:0xf bank_mask:0xf
	v_mov_b32_dpp v75, v75 row_ror:8 row_mask:0xf bank_mask:0xf
	v_mov_b32_dpp v76, v76 row_ror:8 row_mask:0xf bank_mask:0xf
	v_mov_b32_dpp v77, v77 row_ror:8 row_mask:0xf bank_mask:0xf
	v_mov_b32_dpp v66, v66 row_ror:8 row_mask:0xf bank_mask:0xf
	v_mov_b32_dpp v67, v67 row_ror:8 row_mask:0xf bank_mask:0xf
	v_mov_b32_dpp v68, v68 row_ror:8 row_mask:0xf bank_mask:0xf
	v_mov_b32_dpp v69, v69 row_ror:8 row_mask:0xf bank_mask:0xf
	s_mov_b32 exec_lo, 0xff00ff00
	s_mov_b32 exec_hi, 0xff00ff00
	v_swap_b32 v126, v122
	v_swap_b32 v127, v123
	v_swap_b32 v128, v124
	v_swap_b32 v129, v125
	v_swap_b32 v114, v110
	v_swap_b32 v115, v111
	v_swap_b32 v116, v112
	v_swap_b32 v117, v113
	v_swap_b32 v118, v106
	v_swap_b32 v119, v107
	v_swap_b32 v120, v108
	v_swap_b32 v121, v109
	v_swap_b32 v98, v94
	v_swap_b32 v99, v95
	v_swap_b32 v100, v96
	v_swap_b32 v101, v97
	v_swap_b32 v102, v90
	v_swap_b32 v103, v91
	v_swap_b32 v104, v92
	v_swap_b32 v105, v93
	v_swap_b32 v82, v78
	v_swap_b32 v83, v79
	v_swap_b32 v84, v80
	v_swap_b32 v85, v81
	v_swap_b32 v86, v74
	v_swap_b32 v87, v75
	v_swap_b32 v88, v76
	v_swap_b32 v89, v77
	v_swap_b32 v70, v66
	v_swap_b32 v71, v67
	v_swap_b32 v72, v68
	v_swap_b32 v73, v69
	s_mov_b64 exec, -1
	s_waitcnt vmcnt(12)
	v_pk_add_f32 v[126:127], v[126:127], v[160:161]
	v_pk_add_f32 v[128:129], v[128:129], v[162:163]
	v_pk_add_f32 v[122:123], v[122:123], v[164:165]
	v_pk_add_f32 v[124:125], v[124:125], v[166:167]
	v_pk_add_f32 v[114:115], v[114:115], v[168:169]
	v_pk_add_f32 v[116:117], v[116:117], v[170:171]
	v_pk_add_f32 v[110:111], v[110:111], v[172:173]
	v_pk_add_f32 v[112:113], v[112:113], v[174:175]
	s_waitcnt vmcnt(8)
	v_pk_add_f32 v[118:119], v[118:119], v[176:177]
	v_pk_add_f32 v[120:121], v[120:121], v[178:179]
	v_pk_add_f32 v[106:107], v[106:107], v[180:181]
	v_pk_add_f32 v[108:109], v[108:109], v[182:183]
	v_pk_add_f32 v[98:99], v[98:99], v[184:185]
	v_pk_add_f32 v[100:101], v[100:101], v[186:187]
	v_pk_add_f32 v[94:95], v[94:95], v[188:189]
	v_pk_add_f32 v[96:97], v[96:97], v[190:191]
	s_waitcnt vmcnt(4)
	v_pk_add_f32 v[102:103], v[102:103], v[192:193]
	v_pk_add_f32 v[104:105], v[104:105], v[194:195]
	v_pk_add_f32 v[90:91], v[90:91], v[208:209]
	v_pk_add_f32 v[92:93], v[92:93], v[210:211]
	v_pk_add_f32 v[82:83], v[82:83], v[212:213]
	v_pk_add_f32 v[84:85], v[84:85], v[214:215]
	v_pk_add_f32 v[78:79], v[78:79], v[216:217]
	v_pk_add_f32 v[80:81], v[80:81], v[218:219]
	s_waitcnt vmcnt(0)
	v_pk_add_f32 v[86:87], v[86:87], v[220:221]
	v_pk_add_f32 v[88:89], v[88:89], v[222:223]
	v_pk_add_f32 v[74:75], v[74:75], v[138:139]
	v_pk_add_f32 v[76:77], v[76:77], v[140:141]
	v_pk_add_f32 v[70:71], v[70:71], v[134:135]
	v_pk_add_f32 v[72:73], v[72:73], v[136:137]
	v_pk_add_f32 v[66:67], v[66:67], v[130:131]
	v_pk_add_f32 v[68:69], v[68:69], v[132:133]
	global_load_dwordx4 v[160:163], v152, s[20:21]
	global_load_dwordx4 v[164:167], v226, s[20:21]
	global_load_dwordx4 v[168:171], v152, s[20:21] offset:512
	global_load_dwordx4 v[172:175], v226, s[20:21] offset:512
	global_load_dwordx4 v[176:179], v153, s[20:21]
	global_load_dwordx4 v[180:183], v227, s[20:21]
	global_load_dwordx4 v[184:187], v153, s[20:21] offset:512
	global_load_dwordx4 v[188:191], v227, s[20:21] offset:512
	global_load_dwordx4 v[192:195], v154, s[20:21]
	global_load_dwordx4 v[208:211], v240, s[20:21]
	global_load_dwordx4 v[212:215], v154, s[20:21] offset:512
	global_load_dwordx4 v[216:219], v240, s[20:21] offset:512
	global_load_dwordx4 v[220:223], v155, s[20:21]
	global_load_dwordx4 v[138:141], v241, s[20:21]
	global_load_dwordx4 v[134:137], v155, s[20:21] offset:512
	global_load_dwordx4 v[130:133], v241, s[20:21] offset:512
	s_nop 4
	v_mov_b32_dpp v58, v58 row_ror:8 row_mask:0xf bank_mask:0xf
	v_mov_b32_dpp v59, v59 row_ror:8 row_mask:0xf bank_mask:0xf
	v_mov_b32_dpp v60, v60 row_ror:8 row_mask:0xf bank_mask:0xf
	v_mov_b32_dpp v61, v61 row_ror:8 row_mask:0xf bank_mask:0xf
	v_mov_b32_dpp v34, v34 row_ror:8 row_mask:0xf bank_mask:0xf
	v_mov_b32_dpp v35, v35 row_ror:8 row_mask:0xf bank_mask:0xf
	v_mov_b32_dpp v36, v36 row_ror:8 row_mask:0xf bank_mask:0xf
	v_mov_b32_dpp v37, v37 row_ror:8 row_mask:0xf bank_mask:0xf
	v_mov_b32_dpp v50, v50 row_ror:8 row_mask:0xf bank_mask:0xf
	v_mov_b32_dpp v51, v51 row_ror:8 row_mask:0xf bank_mask:0xf
	v_mov_b32_dpp v52, v52 row_ror:8 row_mask:0xf bank_mask:0xf
	v_mov_b32_dpp v53, v53 row_ror:8 row_mask:0xf bank_mask:0xf
	v_mov_b32_dpp v22, v22 row_ror:8 row_mask:0xf bank_mask:0xf
	v_mov_b32_dpp v23, v23 row_ror:8 row_mask:0xf bank_mask:0xf
	v_mov_b32_dpp v24, v24 row_ror:8 row_mask:0xf bank_mask:0xf
	v_mov_b32_dpp v25, v25 row_ror:8 row_mask:0xf bank_mask:0xf
	v_mov_b32_dpp v38, v38 row_ror:8 row_mask:0xf bank_mask:0xf
	v_mov_b32_dpp v39, v39 row_ror:8 row_mask:0xf bank_mask:0xf
	v_mov_b32_dpp v40, v40 row_ror:8 row_mask:0xf bank_mask:0xf
	v_mov_b32_dpp v41, v41 row_ror:8 row_mask:0xf bank_mask:0xf
	v_mov_b32_dpp v8, v8 row_ror:8 row_mask:0xf bank_mask:0xf
	v_mov_b32_dpp v9, v9 row_ror:8 row_mask:0xf bank_mask:0xf
	v_mov_b32_dpp v10, v10 row_ror:8 row_mask:0xf bank_mask:0xf
	v_mov_b32_dpp v11, v11 row_ror:8 row_mask:0xf bank_mask:0xf
	v_mov_b32_dpp v18, v18 row_ror:8 row_mask:0xf bank_mask:0xf
	v_mov_b32_dpp v19, v19 row_ror:8 row_mask:0xf bank_mask:0xf
	v_mov_b32_dpp v20, v20 row_ror:8 row_mask:0xf bank_mask:0xf
	v_mov_b32_dpp v21, v21 row_ror:8 row_mask:0xf bank_mask:0xf
	v_mov_b32_dpp v0, v0 row_ror:8 row_mask:0xf bank_mask:0xf
	v_mov_b32_dpp v1, v1 row_ror:8 row_mask:0xf bank_mask:0xf
	v_mov_b32_dpp v2, v2 row_ror:8 row_mask:0xf bank_mask:0xf
	v_mov_b32_dpp v3, v3 row_ror:8 row_mask:0xf bank_mask:0xf
	s_mov_b32 exec_lo, 0xff00ff00
	s_mov_b32 exec_hi, 0xff00ff00
	v_swap_b32 v62, v58
	v_swap_b32 v63, v59
	v_swap_b32 v64, v60
	v_swap_b32 v65, v61
	v_swap_b32 v42, v34
	v_swap_b32 v43, v35
	v_swap_b32 v44, v36
	v_swap_b32 v45, v37
	v_swap_b32 v54, v50
	v_swap_b32 v55, v51
	v_swap_b32 v56, v52
	v_swap_b32 v57, v53
	v_swap_b32 v26, v22
	v_swap_b32 v27, v23
	v_swap_b32 v28, v24
	v_swap_b32 v29, v25
	v_swap_b32 v46, v38
	v_swap_b32 v47, v39
	v_swap_b32 v48, v40
	v_swap_b32 v49, v41
	v_swap_b32 v12, v8
	v_swap_b32 v13, v9
	v_swap_b32 v14, v10
	v_swap_b32 v15, v11
	v_swap_b32 v30, v18
	v_swap_b32 v31, v19
	v_swap_b32 v32, v20
	v_swap_b32 v33, v21
	v_swap_b32 v4, v0
	v_swap_b32 v5, v1
	v_swap_b32 v6, v2
	v_swap_b32 v7, v3
	s_mov_b64 exec, -1
	global_store_dwordx4 v148, v[126:129], s[20:21]
	global_store_dwordx4 v196, v[122:125], s[20:21]
	global_store_dwordx4 v148, v[114:117], s[20:21] offset:512
	global_store_dwordx4 v196, v[110:113], s[20:21] offset:512
	global_store_dwordx4 v149, v[118:121], s[20:21]
	global_store_dwordx4 v197, v[106:109], s[20:21]
	global_store_dwordx4 v149, v[98:101], s[20:21] offset:512
	global_store_dwordx4 v197, v[94:97], s[20:21] offset:512
	global_store_dwordx4 v150, v[102:105], s[20:21]
	global_store_dwordx4 v224, v[90:93], s[20:21]
	global_store_dwordx4 v150, v[82:85], s[20:21] offset:512
	global_store_dwordx4 v224, v[78:81], s[20:21] offset:512
	global_store_dwordx4 v151, v[86:89], s[20:21]
	global_store_dwordx4 v225, v[74:77], s[20:21]
	global_store_dwordx4 v151, v[70:73], s[20:21] offset:512
	global_store_dwordx4 v225, v[66:69], s[20:21] offset:512
	s_waitcnt vmcnt(0)
	v_pk_add_f32 v[62:63], v[62:63], v[160:161]
	v_pk_add_f32 v[64:65], v[64:65], v[162:163]
	v_pk_add_f32 v[58:59], v[58:59], v[164:165]
	v_pk_add_f32 v[60:61], v[60:61], v[166:167]
	v_pk_add_f32 v[42:43], v[42:43], v[168:169]
	v_pk_add_f32 v[44:45], v[44:45], v[170:171]
	v_pk_add_f32 v[34:35], v[34:35], v[172:173]
	v_pk_add_f32 v[36:37], v[36:37], v[174:175]
	v_pk_add_f32 v[54:55], v[54:55], v[176:177]
	v_pk_add_f32 v[56:57], v[56:57], v[178:179]
	v_pk_add_f32 v[50:51], v[50:51], v[180:181]
	v_pk_add_f32 v[52:53], v[52:53], v[182:183]
	v_pk_add_f32 v[26:27], v[26:27], v[184:185]
	v_pk_add_f32 v[28:29], v[28:29], v[186:187]
	v_pk_add_f32 v[22:23], v[22:23], v[188:189]
	v_pk_add_f32 v[24:25], v[24:25], v[190:191]
	v_pk_add_f32 v[46:47], v[46:47], v[192:193]
	v_pk_add_f32 v[48:49], v[48:49], v[194:195]
	v_pk_add_f32 v[38:39], v[38:39], v[208:209]
	v_pk_add_f32 v[40:41], v[40:41], v[210:211]
	v_pk_add_f32 v[12:13], v[12:13], v[212:213]
	v_pk_add_f32 v[14:15], v[14:15], v[214:215]
	v_pk_add_f32 v[8:9], v[8:9], v[216:217]
	v_pk_add_f32 v[10:11], v[10:11], v[218:219]
	v_pk_add_f32 v[30:31], v[30:31], v[220:221]
	v_pk_add_f32 v[32:33], v[32:33], v[222:223]
	v_pk_add_f32 v[18:19], v[18:19], v[138:139]
	v_pk_add_f32 v[20:21], v[20:21], v[140:141]
	v_pk_add_f32 v[4:5], v[4:5], v[134:135]
	v_pk_add_f32 v[6:7], v[6:7], v[136:137]
	v_pk_add_f32 v[0:1], v[0:1], v[130:131]
	v_pk_add_f32 v[2:3], v[2:3], v[132:133]
	global_store_dwordx4 v152, v[62:65], s[20:21]
	global_store_dwordx4 v226, v[58:61], s[20:21]
	global_store_dwordx4 v152, v[42:45], s[20:21] offset:512
	global_store_dwordx4 v226, v[34:37], s[20:21] offset:512
	global_store_dwordx4 v153, v[54:57], s[20:21]
	global_store_dwordx4 v227, v[50:53], s[20:21]
	global_store_dwordx4 v153, v[26:29], s[20:21] offset:512
	global_store_dwordx4 v227, v[22:25], s[20:21] offset:512
	global_store_dwordx4 v154, v[46:49], s[20:21]
	global_store_dwordx4 v240, v[38:41], s[20:21]
	global_store_dwordx4 v154, v[12:15], s[20:21] offset:512
	global_store_dwordx4 v240, v[8:11], s[20:21] offset:512
	global_store_dwordx4 v155, v[30:33], s[20:21]
	global_store_dwordx4 v241, v[18:21], s[20:21]
	global_store_dwordx4 v155, v[4:7], s[20:21] offset:512
	global_store_dwordx4 v241, v[0:3], s[20:21] offset:512
	v_readlane_b32 s82, v255, 5
	s_and_b64 vcc, exec, s[38:39]
	s_mov_b32 s2, s4
	s_mov_b32 s18, s8
	s_mov_b64 s[40:41], s[16:17]
	s_mov_b64 s[22:23], s[14:15]
	v_readlane_b32 s83, v255, 6
	s_cbranch_vccz .LBB0_167
	s_waitcnt vmcnt(0)
	s_cmpk_gt_u32 s35, 0xff
	s_cbranch_scc1 .LBB0_178
	s_barrier
